# NA prologue: bias-table loads unrolled and tile-0 K/V loads hoisted (one memory round trip instead of six)
# speedup vs baseline: 1.0007x; 1.0007x over previous
; template <int VAR> __device__ __forceinline__ void na_unit(const bf16* __restrict__ proj, bf16* mix, const float* __restrict__ relb, int b, int h, int rg, char* lds) {
;     ...
;   __syncthreads();
;   for (int i = tid; i < 15 * NA_BSTRIDE; i += 512) { const int ri = i >> 7, ci = (i & 127) - 48; bl[i] = (ci >= 0 && ci < 31) ? relb[(h * 15 + ri) * 31 + ci] * 1.4426950408889634f : 0.f; }
.LBB0_508:
	s_lshl_b32 s0, s89, 2
	s_and_b32 s10, s0, 60
	v_mov_b32_e32 v170, v0
	v_sub_u32_e64 v2, s10, 1 clamp
	s_movk_i32 s0, 0x780
	s_bfe_u32 s97, s89, 0x30004
	v_readfirstlane_b32 s12, v2
	v_readfirstlane_b32 s2, v170
	v_cmp_gt_i32_e32 vcc, s0, v170
	s_barrier
	s_and_saveexec_b64 s[4:5], vcc
	s_cbranch_execz .LBB0_513
	v_and_b32_e32 v146, 0x7f, v170
	v_subrev_u32_e32 v2, 48, v146
	s_mul_i32 s8, s97, 15
	v_cmp_gt_u32_e32 vcc, 31, v2
	v_lshl_add_u32 v66, v170, 2, s65
	v_mov_b32_e32 v60, 0
	v_mov_b32_e32 v61, 0
	v_mov_b32_e32 v62, 0
	v_mov_b32_e32 v63, 0
	s_and_saveexec_b64 s[0:1], vcc
	s_cbranch_execz .Lnab_issued
	v_ashrrev_i32_e32 v64, 7, v170
	v_add_u32_e32 v64, s8, v64
	v_mul_lo_u32 v64, v64, 31
	v_ashrrev_i32_e32 v65, 31, v64
	v_lshl_add_u64 v[64:65], v[64:65], 0, v[146:147]
	v_lshl_add_u64 v[64:65], v[64:65], 2, s[56:57]
	global_load_dword v60, v[64:65], off offset:-192
	global_load_dword v61, v[64:65], off offset:304
	global_load_dword v62, v[64:65], off offset:800
	v_cmp_gt_u32_e32 vcc, 0x180, v170
	s_and_b64 exec, exec, vcc
	global_load_dword v63, v[64:65], off offset:1296

; __device__ __forceinline__ int v_st(int k, int c) { const int kk = (k & ~0xC) | ((k & 4) << 1) | ((k & 8) >> 1); return ((kk >> 3) * 4 + (c >> 5)) * 512 + ((kk & 7) * 32 + (c & 31)) * 2; }
; __device__ __forceinline__ int v_rd_base(int lane) { return ((lane & 3) << 3) | (((lane >> 2) & 3) << 6) | (((lane >> 4) & 1) << 5) | (((lane >> 5) & 1) << 8); }
; template <int VAR> __device__ __forceinline__ void na_unit(const bf16* __restrict__ proj, bf16* mix, const float* __restrict__ relb, int b, int h, int rg, char* lds) {
;     ...
;   const long tok0 = (long)b * SEQ;
;   const int r0 = rg * 4, gr = r0 + (wid >> 1), cq = 32 * (wid & 1) + r32;
;   const int jlo = min(max(r0 - 4, 0), 56), jhi = min(max(r0 - 1, 0), 56) + 7, NT = (VAR == 1) ? 1 : jhi - jlo + 1;
;   const int mlo = min(max(gr - 4, 0), 56);
;   const int cs = min(max(cq - 8, 0), 48);
;   const int mbase = 4 * hi - cs;
;   const char* blane0 = (const char*)(bl + 48 + 15 - cq + 4 * hi);
;   const int sr = tid >> 4, sc = (tid & 15) * 8, vst0 = v_st(sr, sc), vst1 = v_st(32 + sr, sc), kst0 = KSWZ128(sr, sc * 2), kst1 = KSWZ128(32 + sr, sc * 2);
;   const int vb0 = (int)(uintptr_t)V_lds + v_rd_base(lane);
;   const bf16* Kh = proj + tok0 * LDP + 2048 + h * 128;
;   const bf16* Vh = proj + tok0 * LDP + 3072 + h * 128;
;   const bf16* Qw = proj + (tok0 + gr * 64 + cq) * LDP + 1024 + h * 128 + hi * 8;
;   __syncthreads();
;   for (int i = tid; i < 15 * NA_BSTRIDE; i += 512) { const int ri = i >> 7, ci = (i & 127) - 48; bl[i] = (ci >= 0 && ci < 31) ? relb[(h * 15 + ri) * 31 + ci] * 1.4426950408889634f : 0.f; }
;   char* Ql = lds + LDS_NAQ + wid * 8192 + lane * 16;
;   { bf16x8 qr[8];
; #pragma unroll
;     for (int d0 = 0; d0 < 8; ++d0) qr[d0] = ld8(Qw + d0 * 16);
; #pragma unroll
;     for (int d0 = 0; d0 < 8; ++d0) *(bf16x8*)(Ql + d0 * 1024) = qr[d0]; }
;   float zf_ = 0.f; asm volatile("" : "+v"(zf_));
;   f32x16 zv_;
; #pragma unroll
;   for (int r = 0; r < 16; ++r) zv_[r] = zf_;
;   float m_reg = -1e30f, l_reg = 0; f32x16 o[4]; o[0] = zv_; o[1] = zv_; o[2] = zv_; o[3] = zv_;
;   bf16x8 vsA0, vsA1, ksA0, ksA1;
;     ...
;   NLOAD(A, jlo * 64); NWRITE(A, 0);
;   if (NT > 1) NLOAD(A, (jlo + 1) * 64);
.LBB0_513:
	s_or_b64 exec, exec, s[4:5]
	s_ashr_i32 s77, s2, 7
	s_add_i32 s1, s77, s10
	s_max_i32 s6, s1, 4
	s_add_i32 s6, s6, -4
	s_bfe_u32 s8, s3, 0x40002
	s_ashr_i32 s11, s2, 6
	s_min_u32 s86, s6, 56
	s_ashr_i32 s6, s89, 7
	s_lshl_b32 s0, s8, 2
	s_and_b32 s51, s11, 1
	s_max_u32 s4, s10, 4
	s_min_u32 s5, s12, 56
	s_ashr_i32 s7, s6, 31
	s_max_u32 s87, s0, 4
	s_lshr_b32 s9, s89, 4
	s_lshl_b32 s0, s51, 5
	s_lshl_b64 s[12:13], s[6:7], 12
	s_lshl_b32 s14, s4, 6
	s_sub_i32 s10, s5, s4
	s_lshl_b64 s[62:63], s[6:7], 25
	s_add_u32 s4, s70, s62
	s_addc_u32 s5, s71, s63
	s_lshl_b32 s58, s97, 8
	s_add_u32 s6, s4, s58
	s_addc_u32 s7, s5, 0
	s_add_u32 s4, s6, 0x1000
	s_addc_u32 s5, s7, 0
	s_add_u32 s6, s6, 0x1800
	s_addc_u32 s7, s7, 0
	s_lshl_b32 s1, s1, 6
	v_and_b32_e32 v160, 31, v170
	s_ashr_i32 s15, s1, 31
	v_or_b32_e32 v2, s0, v160
	s_add_u32 s96, s12, s1
	v_sub_u32_e64 v3, v2, 8 clamp
	s_addc_u32 s1, s13, s15
	v_min_u32_e32 v18, 48, v3
	v_or_b32_e32 v2, s96, v2
	v_mov_b32_e32 v3, s1
	v_lshlrev_b64 v[2:3], 13, v[2:3]
	v_bfe_u32 v161, v170, 5, 1
	v_lshl_add_u64 v[2:3], s[70:71], 0, v[2:3]
	v_lshl_add_u64 v[2:3], v[2:3], 0, s[58:59]
	v_lshlrev_b32_e32 v150, 4, v161
	v_mov_b32_e32 v151, v147
	v_lshl_add_u64 v[2:3], v[2:3], 0, v[150:151]
	global_load_dwordx4 v[6:9], v[2:3], off offset:2048
	global_load_dwordx4 v[10:13], v[2:3], off offset:2080
	global_load_dwordx4 v[14:17], v[2:3], off offset:2112
	global_load_dwordx4 v[20:23], v[2:3], off offset:2144
	global_load_dwordx4 v[24:27], v[2:3], off offset:2176
	global_load_dwordx4 v[28:31], v[2:3], off offset:2208
	global_load_dwordx4 v[32:35], v[2:3], off offset:2240
	global_load_dwordx4 v[36:39], v[2:3], off offset:2272
	v_and_b32_e32 v149, 63, v170
	v_ashrrev_i32_e32 v171, 4, v170
	s_lshl_b32 s11, s11, 13
	s_addk_i32 s14, 0xff00
	v_lshlrev_b32_e32 v3, 3, v170
	v_lshlrev_b32_e32 v19, 4, v149
	s_add_i32 s58, s11, 0
	v_add_u32_e32 v4, s14, v171
	v_and_b32_e32 v151, 0x78, v3
	v_add_u32_e32 v41, s58, v19
	v_ashrrev_i32_e32 v5, 31, v4
	v_add_u32_e32 v40, 32, v4
	v_lshlrev_b32_e32 v148, 1, v151
	v_add_u32_e32 v162, 0x12800, v41
	v_lshlrev_b64 v[42:43], 13, v[4:5]
	v_ashrrev_i32_e32 v41, 31, v40
	v_or_b32_e32 v42, v42, v148
	v_lshlrev_b64 v[40:41], 13, v[40:41]
	v_mov_b32_e32 v2, 0
	v_lshl_add_u64 v[44:45], s[6:7], 0, v[42:43]
	v_or_b32_e32 v40, v40, v148
	v_lshl_add_u64 v[42:43], s[4:5], 0, v[42:43]
	v_lshl_add_u64 v[46:47], s[6:7], 0, v[40:41]
	v_lshl_add_u64 v[40:41], s[4:5], 0, v[40:41]
	v_and_b32_e32 v5, 0x70, v170
	v_bfe_u32 v3, v3, 5, 2
	s_cmp_gt_i32 s10, -11
	global_load_dwordx4 v[114:117], v[44:45], off
	global_load_dwordx4 v[118:121], v[46:47], off
	global_load_dwordx4 v[122:125], v[42:43], off
	global_load_dwordx4 v[126:129], v[40:41], off
	s_waitcnt vmcnt(12)
	v_mul_f32_e32 v60, 0x3fb8aa3b, v60
	v_mul_f32_e32 v61, 0x3fb8aa3b, v61
	v_mul_f32_e32 v62, 0x3fb8aa3b, v62
	v_mul_f32_e32 v63, 0x3fb8aa3b, v63
	ds_write_b32 v66, v60
	ds_write_b32 v66, v61 offset:2048
	ds_write_b32 v66, v62 offset:4096
	ds_write_b32 v66, v63 offset:6144
	s_waitcnt vmcnt(11)
	ds_write_b128 v162, v[6:9]
	s_waitcnt vmcnt(10)
	ds_write_b128 v162, v[10:13] offset:1024
	s_waitcnt vmcnt(9)
	ds_write_b128 v162, v[14:17] offset:2048
	s_waitcnt vmcnt(8)
	ds_write_b128 v162, v[20:23] offset:3072
	s_waitcnt vmcnt(7)
	ds_write_b128 v162, v[24:27] offset:4096
	s_waitcnt vmcnt(6)
	ds_write_b128 v162, v[28:31] offset:5120
	s_waitcnt vmcnt(5)
	ds_write_b128 v162, v[32:35] offset:6144
	s_waitcnt vmcnt(4)
	ds_write_b128 v162, v[36:39] offset:7168
	v_and_b32_e32 v6, 0xfffff0, v171
	v_lshlrev_b32_e32 v7, 1, v171
	v_lshrrev_b32_e32 v8, 1, v171
	v_and_b32_e32 v9, 3, v171
	v_add_u32_e32 v10, 32, v171
	v_and_or_b32 v6, v7, 8, v6
	v_and_or_b32 v7, v8, 4, v9
	v_and_b32_e32 v8, 0xfffff0, v10
	v_lshlrev_b32_e32 v9, 1, v10
	v_and_or_b32 v8, v9, 8, v8
	v_lshlrev_b32_e32 v11, 8, v171
	v_lshlrev_b32_e32 v10, 8, v10
	v_lshrrev_b32_e32 v6, 1, v6
	v_lshrrev_b32_e32 v8, 1, v8
	v_bitop3_b32 v9, v148, v11, v5 bitop3:0xde
	v_bitop3_b32 v5, v148, v10, v5 bitop3:0xde
	v_or_b32_e32 v6, v6, v3
	v_or_b32_e32 v3, v8, v3
	v_lshlrev_b32_e32 v7, 6, v7
	v_and_b32_e32 v12, 48, v148
	v_add_u32_e32 v164, 0, v5
	v_lshlrev_b32_e32 v5, 9, v6
	v_lshlrev_b32_e32 v3, 9, v3
	v_or3_b32 v5, v5, v7, v12
	v_or3_b32 v3, v3, v7, v12
	v_add_u32_e32 v163, 0, v9
	v_add_u32_e32 v165, 0, v5
	v_add_u32_e32 v166, 0, v3
	s_waitcnt vmcnt(3)
	ds_write_b128 v165, v[114:117]
	s_waitcnt vmcnt(2)
	ds_write_b128 v166, v[118:121]
	s_waitcnt vmcnt(1)
	ds_write_b128 v163, v[122:125] offset:32768
	s_waitcnt vmcnt(0)
	ds_write_b128 v164, v[126:129] offset:32768
	s_cbranch_scc0 .LBB0_515
	v_add_u32_e32 v6, 64, v4
	v_ashrrev_i32_e32 v7, 31, v6
	v_add_u32_e32 v4, 0x60, v4
	v_lshlrev_b64 v[6:7], 13, v[6:7]
	v_ashrrev_i32_e32 v5, 31, v4
	v_or_b32_e32 v6, v6, v148
	v_lshlrev_b64 v[4:5], 13, v[4:5]
	v_lshl_add_u64 v[8:9], s[6:7], 0, v[6:7]
	v_or_b32_e32 v4, v4, v148
	v_lshl_add_u64 v[6:7], s[4:5], 0, v[6:7]
	v_lshl_add_u64 v[10:11], s[6:7], 0, v[4:5]
	global_load_dwordx4 v[114:117], v[8:9], off
	global_load_dwordx4 v[118:121], v[10:11], off
	v_lshl_add_u64 v[4:5], s[4:5], 0, v[4:5]
	global_load_dwordx4 v[122:125], v[6:7], off
	global_load_dwordx4 v[126:129], v[4:5], off
